# merge-GEMM gated epilogue: 16 gate loads issued up front (global, counted vmcnt), packed f32 math, stores at end
# speedup vs baseline: 1.0305x; 1.0305x over previous
; DI unsigned pk_bf16(float lo, float hi) { unsigned r; asm("v_cvt_pk_bf16_f32 %0, %1, %2" : "=v"(r) : "v"(lo), "v"(hi)); return r; }
; DI float lo_f(unsigned w) { return __uint_as_float(w << 16); }
; DI float hi_f(unsigned w) { return __uint_as_float(w & 0xffff0000u); }
; DI float sigmoidf_(float x) { return __builtin_amdgcn_rcpf(1.f + __expf(-x)); }
;     DI void operator()(const f32x4 (&acc)[2][2][4][2], const Unit& u, int wr, int wc, int fr, int fq, LAS unsigned char* lds) const {
;     ...
;             bf16_t* Gb = (bf16_t*)(ws + WS_P) + C_MG + (size_t)u.pm * BM * IN_DIM + u.pn * BM;
; #pragma unroll
;             for (int ai = 0; ai < 2; ++ai)
; #pragma unroll
;                 for (int m = 0; m < 4; ++m)
; #pragma unroll
;                     for (int bj = 0; bj < 2; ++bj) {
;                         bf16_t* gp = Gb + ((rl0 + ai * HALF + m * 16) * (unsigned)IN_DIM + cl0 + bj * HALF);
;                         const u32x4 gv = *(const u32x4*)gp;
;                         const f32x4 v0 = acc[ai][bj][m][0], v1 = acc[ai][bj][m][1];
;                         u32x4 o;
;                         o[0] = pk_bf16(v0[0] * sigmoidf_(lo_f(gv[0])), v0[1] * sigmoidf_(hi_f(gv[0]))); o[1] = pk_bf16(v0[2] * sigmoidf_(lo_f(gv[1])), v0[3] * sigmoidf_(hi_f(gv[1])));
;                         o[2] = pk_bf16(v1[0] * sigmoidf_(lo_f(gv[2])), v1[1] * sigmoidf_(hi_f(gv[2]))); o[3] = pk_bf16(v1[2] * sigmoidf_(lo_f(gv[3])), v1[3] * sigmoidf_(hi_f(gv[3])));
;                         *(u32x4*)gp = o; }
.LBB0_328:
	s_and_b64 vcc, exec, s[20:21]
	s_cbranch_vccz .LBB0_330
	s_mul_i32 s21, s10, 0x264000
	s_mul_hi_i32 s20, s10, 0x264000
	s_add_u32 s21, s18, s21
	s_addc_u32 s20, s19, s20
	s_ashr_i32 s49, s48, 31
	s_lshl_b64 s[18:19], s[48:49], 1
	s_add_u32 s18, s21, s18
	s_addc_u32 s19, s20, s19
	s_add_u32 s42, s18, 0xb0e2e40
	s_addc_u32 s43, s19, 0
	s_movk_i32 s18, 0x1320
	v_mad_u32_u24 v130, v187, s18, v146
	v_lshlrev_b32_e32 v130, 1, v130
	v_add_u32_e32 v131, 0x26400, v130
	v_add_u32_e32 v132, 0x4c800, v130
	v_add_u32_e32 v133, 0x72c00, v130
	v_add_u32_e32 v179, 0x132000, v130
	v_add_u32_e32 v180, 0x158400, v130
	v_add_u32_e32 v240, 0x17e800, v130
	v_add_u32_e32 v241, 0x1a4c00, v130
	global_load_dwordx4 v[148:151], v130, s[42:43]
	global_load_dwordx4 v[152:155], v130, s[42:43] offset:256
	global_load_dwordx4 v[156:159], v131, s[42:43]
	global_load_dwordx4 v[160:163], v131, s[42:43] offset:256
	global_load_dwordx4 v[164:167], v132, s[42:43]
	global_load_dwordx4 v[168:171], v132, s[42:43] offset:256
	global_load_dwordx4 v[172:175], v133, s[42:43]
	global_load_dwordx4 v[190:193], v133, s[42:43] offset:256
	global_load_dwordx4 v[194:197], v179, s[42:43]
	global_load_dwordx4 v[198:201], v179, s[42:43] offset:256
	global_load_dwordx4 v[202:205], v180, s[42:43]
	global_load_dwordx4 v[206:209], v180, s[42:43] offset:256
	global_load_dwordx4 v[210:213], v240, s[42:43]
	global_load_dwordx4 v[214:217], v240, s[42:43] offset:256
	global_load_dwordx4 v[218:221], v241, s[42:43]
	global_load_dwordx4 v[222:225], v241, s[42:43] offset:256
	s_mov_b32 s18, 0xbfb8aa3b
	s_mov_b32 s20, 1.0
	s_waitcnt lgkmcnt(0)
	s_waitcnt vmcnt(15)
	v_lshlrev_b32_e32 v226, 16, v148
	v_and_b32_e32 v227, 0xffff0000, v148
	v_lshlrev_b32_e32 v228, 16, v149
	v_and_b32_e32 v229, 0xffff0000, v149
	v_lshlrev_b32_e32 v230, 16, v150
	v_and_b32_e32 v231, 0xffff0000, v150
	v_lshlrev_b32_e32 v248, 16, v151
	v_and_b32_e32 v249, 0xffff0000, v151
	v_pk_mul_f32 v[226:227], v[226:227], s[18:19] op_sel_hi:[1,0]
	v_pk_mul_f32 v[228:229], v[228:229], s[18:19] op_sel_hi:[1,0]
	v_pk_mul_f32 v[230:231], v[230:231], s[18:19] op_sel_hi:[1,0]
	v_pk_mul_f32 v[248:249], v[248:249], s[18:19] op_sel_hi:[1,0]
	v_exp_f32_e32 v226, v226
	v_exp_f32_e32 v227, v227
	v_exp_f32_e32 v228, v228
	v_exp_f32_e32 v229, v229
	v_exp_f32_e32 v230, v230
	v_exp_f32_e32 v231, v231
	v_exp_f32_e32 v248, v248
	v_exp_f32_e32 v249, v249
	v_pk_add_f32 v[226:227], v[226:227], s[20:21] op_sel_hi:[1,0]
	v_pk_add_f32 v[228:229], v[228:229], s[20:21] op_sel_hi:[1,0]
	v_pk_add_f32 v[230:231], v[230:231], s[20:21] op_sel_hi:[1,0]
	v_pk_add_f32 v[248:249], v[248:249], s[20:21] op_sel_hi:[1,0]
	v_rcp_f32_e32 v226, v226
	v_rcp_f32_e32 v227, v227
	v_rcp_f32_e32 v228, v228
	v_rcp_f32_e32 v229, v229
	v_rcp_f32_e32 v230, v230
	v_rcp_f32_e32 v231, v231
	v_rcp_f32_e32 v248, v248
	v_rcp_f32_e32 v249, v249
	v_pk_mul_f32 v[226:227], v[226:227], v[126:127]
	v_pk_mul_f32 v[228:229], v[228:229], v[128:129]
	v_pk_mul_f32 v[230:231], v[230:231], v[122:123]
	v_pk_mul_f32 v[248:249], v[248:249], v[124:125]
	v_cvt_pk_bf16_f32 v148, v226, v227
	v_cvt_pk_bf16_f32 v149, v228, v229
	v_cvt_pk_bf16_f32 v150, v230, v231
	v_cvt_pk_bf16_f32 v151, v248, v249
	s_waitcnt vmcnt(14)
	v_lshlrev_b32_e32 v226, 16, v152
	v_and_b32_e32 v227, 0xffff0000, v152
	v_lshlrev_b32_e32 v228, 16, v153
	v_and_b32_e32 v229, 0xffff0000, v153
	v_lshlrev_b32_e32 v230, 16, v154
	v_and_b32_e32 v231, 0xffff0000, v154
	v_lshlrev_b32_e32 v248, 16, v155
	v_and_b32_e32 v249, 0xffff0000, v155
	v_pk_mul_f32 v[226:227], v[226:227], s[18:19] op_sel_hi:[1,0]
	v_pk_mul_f32 v[228:229], v[228:229], s[18:19] op_sel_hi:[1,0]
	v_pk_mul_f32 v[230:231], v[230:231], s[18:19] op_sel_hi:[1,0]
	v_pk_mul_f32 v[248:249], v[248:249], s[18:19] op_sel_hi:[1,0]
	v_exp_f32_e32 v226, v226
	v_exp_f32_e32 v227, v227
	v_exp_f32_e32 v228, v228
	v_exp_f32_e32 v229, v229
	v_exp_f32_e32 v230, v230
	v_exp_f32_e32 v231, v231
	v_exp_f32_e32 v248, v248
	v_exp_f32_e32 v249, v249
	v_pk_add_f32 v[226:227], v[226:227], s[20:21] op_sel_hi:[1,0]
	v_pk_add_f32 v[228:229], v[228:229], s[20:21] op_sel_hi:[1,0]
	v_pk_add_f32 v[230:231], v[230:231], s[20:21] op_sel_hi:[1,0]
	v_pk_add_f32 v[248:249], v[248:249], s[20:21] op_sel_hi:[1,0]
	v_rcp_f32_e32 v226, v226
	v_rcp_f32_e32 v227, v227
	v_rcp_f32_e32 v228, v228
	v_rcp_f32_e32 v229, v229
	v_rcp_f32_e32 v230, v230
	v_rcp_f32_e32 v231, v231
	v_rcp_f32_e32 v248, v248
	v_rcp_f32_e32 v249, v249
	v_pk_mul_f32 v[226:227], v[226:227], v[110:111]
	v_pk_mul_f32 v[228:229], v[228:229], v[112:113]
	v_pk_mul_f32 v[230:231], v[230:231], v[102:103]
	v_pk_mul_f32 v[248:249], v[248:249], v[104:105]
	v_cvt_pk_bf16_f32 v152, v226, v227
	v_cvt_pk_bf16_f32 v153, v228, v229
	v_cvt_pk_bf16_f32 v154, v230, v231
	v_cvt_pk_bf16_f32 v155, v248, v249
	s_waitcnt vmcnt(13)
	v_lshlrev_b32_e32 v226, 16, v156
	v_and_b32_e32 v227, 0xffff0000, v156
	v_lshlrev_b32_e32 v228, 16, v157
	v_and_b32_e32 v229, 0xffff0000, v157
	v_lshlrev_b32_e32 v230, 16, v158
	v_and_b32_e32 v231, 0xffff0000, v158
	v_lshlrev_b32_e32 v248, 16, v159
	v_and_b32_e32 v249, 0xffff0000, v159
	v_pk_mul_f32 v[226:227], v[226:227], s[18:19] op_sel_hi:[1,0]
	v_pk_mul_f32 v[228:229], v[228:229], s[18:19] op_sel_hi:[1,0]
	v_pk_mul_f32 v[230:231], v[230:231], s[18:19] op_sel_hi:[1,0]
	v_pk_mul_f32 v[248:249], v[248:249], s[18:19] op_sel_hi:[1,0]
	v_exp_f32_e32 v226, v226
	v_exp_f32_e32 v227, v227
	v_exp_f32_e32 v228, v228
	v_exp_f32_e32 v229, v229
	v_exp_f32_e32 v230, v230
	v_exp_f32_e32 v231, v231
	v_exp_f32_e32 v248, v248
	v_exp_f32_e32 v249, v249
	v_pk_add_f32 v[226:227], v[226:227], s[20:21] op_sel_hi:[1,0]
	v_pk_add_f32 v[228:229], v[228:229], s[20:21] op_sel_hi:[1,0]
	v_pk_add_f32 v[230:231], v[230:231], s[20:21] op_sel_hi:[1,0]
	v_pk_add_f32 v[248:249], v[248:249], s[20:21] op_sel_hi:[1,0]
	v_rcp_f32_e32 v226, v226
	v_rcp_f32_e32 v227, v227
	v_rcp_f32_e32 v228, v228
	v_rcp_f32_e32 v229, v229
	v_rcp_f32_e32 v230, v230
	v_rcp_f32_e32 v231, v231
	v_rcp_f32_e32 v248, v248
	v_rcp_f32_e32 v249, v249
	v_pk_mul_f32 v[226:227], v[226:227], v[118:119]
	v_pk_mul_f32 v[228:229], v[228:229], v[120:121]
	v_pk_mul_f32 v[230:231], v[230:231], v[114:115]
	v_pk_mul_f32 v[248:249], v[248:249], v[116:117]
	v_cvt_pk_bf16_f32 v156, v226, v227
	v_cvt_pk_bf16_f32 v157, v228, v229
	v_cvt_pk_bf16_f32 v158, v230, v231
	v_cvt_pk_bf16_f32 v159, v248, v249
	s_waitcnt vmcnt(12)
; DI unsigned pk_bf16(float lo, float hi) { unsigned r; asm("v_cvt_pk_bf16_f32 %0, %1, %2" : "=v"(r) : "v"(lo), "v"(hi)); return r; }
; DI float lo_f(unsigned w) { return __uint_as_float(w << 16); }
; DI float hi_f(unsigned w) { return __uint_as_float(w & 0xffff0000u); }
; DI float sigmoidf_(float x) { return __builtin_amdgcn_rcpf(1.f + __expf(-x)); }
;     DI void operator()(const f32x4 (&acc)[2][2][4][2], const Unit& u, int wr, int wc, int fr, int fq, LAS unsigned char* lds) const {
;     ...
;                     for (int bj = 0; bj < 2; ++bj) {
;                         bf16_t* gp = Gb + ((rl0 + ai * HALF + m * 16) * (unsigned)IN_DIM + cl0 + bj * HALF);
;                         const u32x4 gv = *(const u32x4*)gp;
;                         const f32x4 v0 = acc[ai][bj][m][0], v1 = acc[ai][bj][m][1];
;                         u32x4 o;
;                         o[0] = pk_bf16(v0[0] * sigmoidf_(lo_f(gv[0])), v0[1] * sigmoidf_(hi_f(gv[0]))); o[1] = pk_bf16(v0[2] * sigmoidf_(lo_f(gv[1])), v0[3] * sigmoidf_(hi_f(gv[1])));
;                         o[2] = pk_bf16(v1[0] * sigmoidf_(lo_f(gv[2])), v1[1] * sigmoidf_(hi_f(gv[2]))); o[3] = pk_bf16(v1[2] * sigmoidf_(lo_f(gv[3])), v1[3] * sigmoidf_(hi_f(gv[3])));
;                         *(u32x4*)gp = o; }
	v_lshlrev_b32_e32 v226, 16, v160
	v_and_b32_e32 v227, 0xffff0000, v160
	v_lshlrev_b32_e32 v228, 16, v161
	v_and_b32_e32 v229, 0xffff0000, v161
	v_lshlrev_b32_e32 v230, 16, v162
	v_and_b32_e32 v231, 0xffff0000, v162
	v_lshlrev_b32_e32 v248, 16, v163
	v_and_b32_e32 v249, 0xffff0000, v163
	v_pk_mul_f32 v[226:227], v[226:227], s[18:19] op_sel_hi:[1,0]
	v_pk_mul_f32 v[228:229], v[228:229], s[18:19] op_sel_hi:[1,0]
	v_pk_mul_f32 v[230:231], v[230:231], s[18:19] op_sel_hi:[1,0]
	v_pk_mul_f32 v[248:249], v[248:249], s[18:19] op_sel_hi:[1,0]
	v_exp_f32_e32 v226, v226
	v_exp_f32_e32 v227, v227
	v_exp_f32_e32 v228, v228
	v_exp_f32_e32 v229, v229
	v_exp_f32_e32 v230, v230
	v_exp_f32_e32 v231, v231
	v_exp_f32_e32 v248, v248
	v_exp_f32_e32 v249, v249
	v_pk_add_f32 v[226:227], v[226:227], s[20:21] op_sel_hi:[1,0]
	v_pk_add_f32 v[228:229], v[228:229], s[20:21] op_sel_hi:[1,0]
	v_pk_add_f32 v[230:231], v[230:231], s[20:21] op_sel_hi:[1,0]
	v_pk_add_f32 v[248:249], v[248:249], s[20:21] op_sel_hi:[1,0]
	v_rcp_f32_e32 v226, v226
	v_rcp_f32_e32 v227, v227
	v_rcp_f32_e32 v228, v228
	v_rcp_f32_e32 v229, v229
	v_rcp_f32_e32 v230, v230
	v_rcp_f32_e32 v231, v231
	v_rcp_f32_e32 v248, v248
	v_rcp_f32_e32 v249, v249
	v_pk_mul_f32 v[226:227], v[226:227], v[94:95]
	v_pk_mul_f32 v[228:229], v[228:229], v[96:97]
	v_pk_mul_f32 v[230:231], v[230:231], v[86:87]
	v_pk_mul_f32 v[248:249], v[248:249], v[88:89]
	v_cvt_pk_bf16_f32 v160, v226, v227
	v_cvt_pk_bf16_f32 v161, v228, v229
	v_cvt_pk_bf16_f32 v162, v230, v231
	v_cvt_pk_bf16_f32 v163, v248, v249
	s_waitcnt vmcnt(11)
	v_lshlrev_b32_e32 v226, 16, v164
	v_and_b32_e32 v227, 0xffff0000, v164
	v_lshlrev_b32_e32 v228, 16, v165
	v_and_b32_e32 v229, 0xffff0000, v165
	v_lshlrev_b32_e32 v230, 16, v166
	v_and_b32_e32 v231, 0xffff0000, v166
	v_lshlrev_b32_e32 v248, 16, v167
	v_and_b32_e32 v249, 0xffff0000, v167
	v_pk_mul_f32 v[226:227], v[226:227], s[18:19] op_sel_hi:[1,0]
	v_pk_mul_f32 v[228:229], v[228:229], s[18:19] op_sel_hi:[1,0]
	v_pk_mul_f32 v[230:231], v[230:231], s[18:19] op_sel_hi:[1,0]
	v_pk_mul_f32 v[248:249], v[248:249], s[18:19] op_sel_hi:[1,0]
	v_exp_f32_e32 v226, v226
	v_exp_f32_e32 v227, v227
	v_exp_f32_e32 v228, v228
	v_exp_f32_e32 v229, v229
	v_exp_f32_e32 v230, v230
	v_exp_f32_e32 v231, v231
	v_exp_f32_e32 v248, v248
	v_exp_f32_e32 v249, v249
	v_pk_add_f32 v[226:227], v[226:227], s[20:21] op_sel_hi:[1,0]
	v_pk_add_f32 v[228:229], v[228:229], s[20:21] op_sel_hi:[1,0]
	v_pk_add_f32 v[230:231], v[230:231], s[20:21] op_sel_hi:[1,0]
	v_pk_add_f32 v[248:249], v[248:249], s[20:21] op_sel_hi:[1,0]
	v_rcp_f32_e32 v226, v226
	v_rcp_f32_e32 v227, v227
	v_rcp_f32_e32 v228, v228
	v_rcp_f32_e32 v229, v229
	v_rcp_f32_e32 v230, v230
	v_rcp_f32_e32 v231, v231
	v_rcp_f32_e32 v248, v248
	v_rcp_f32_e32 v249, v249
	v_pk_mul_f32 v[226:227], v[226:227], v[106:107]
	v_pk_mul_f32 v[228:229], v[228:229], v[108:109]
	v_pk_mul_f32 v[230:231], v[230:231], v[98:99]
	v_pk_mul_f32 v[248:249], v[248:249], v[100:101]
	v_cvt_pk_bf16_f32 v164, v226, v227
	v_cvt_pk_bf16_f32 v165, v228, v229
	v_cvt_pk_bf16_f32 v166, v230, v231
	v_cvt_pk_bf16_f32 v167, v248, v249
	s_waitcnt vmcnt(10)
	v_lshlrev_b32_e32 v226, 16, v168
	v_and_b32_e32 v227, 0xffff0000, v168
	v_lshlrev_b32_e32 v228, 16, v169
	v_and_b32_e32 v229, 0xffff0000, v169
	v_lshlrev_b32_e32 v230, 16, v170
	v_and_b32_e32 v231, 0xffff0000, v170
	v_lshlrev_b32_e32 v248, 16, v171
	v_and_b32_e32 v249, 0xffff0000, v171
	v_pk_mul_f32 v[226:227], v[226:227], s[18:19] op_sel_hi:[1,0]
	v_pk_mul_f32 v[228:229], v[228:229], s[18:19] op_sel_hi:[1,0]
	v_pk_mul_f32 v[230:231], v[230:231], s[18:19] op_sel_hi:[1,0]
	v_pk_mul_f32 v[248:249], v[248:249], s[18:19] op_sel_hi:[1,0]
	v_exp_f32_e32 v226, v226
	v_exp_f32_e32 v227, v227
	v_exp_f32_e32 v228, v228
	v_exp_f32_e32 v229, v229
	v_exp_f32_e32 v230, v230
	v_exp_f32_e32 v231, v231
	v_exp_f32_e32 v248, v248
	v_exp_f32_e32 v249, v249
	v_pk_add_f32 v[226:227], v[226:227], s[20:21] op_sel_hi:[1,0]
	v_pk_add_f32 v[228:229], v[228:229], s[20:21] op_sel_hi:[1,0]
	v_pk_add_f32 v[230:231], v[230:231], s[20:21] op_sel_hi:[1,0]
	v_pk_add_f32 v[248:249], v[248:249], s[20:21] op_sel_hi:[1,0]
	v_rcp_f32_e32 v226, v226
	v_rcp_f32_e32 v227, v227
	v_rcp_f32_e32 v228, v228
	v_rcp_f32_e32 v229, v229
	v_rcp_f32_e32 v230, v230
	v_rcp_f32_e32 v231, v231
	v_rcp_f32_e32 v248, v248
	v_rcp_f32_e32 v249, v249
	v_pk_mul_f32 v[226:227], v[226:227], v[78:79]
	v_pk_mul_f32 v[228:229], v[228:229], v[80:81]
	v_pk_mul_f32 v[230:231], v[230:231], v[74:75]
	v_pk_mul_f32 v[248:249], v[248:249], v[76:77]
	v_cvt_pk_bf16_f32 v168, v226, v227
	v_cvt_pk_bf16_f32 v169, v228, v229
	v_cvt_pk_bf16_f32 v170, v230, v231
	v_cvt_pk_bf16_f32 v171, v248, v249
	s_waitcnt vmcnt(9)
	v_lshlrev_b32_e32 v226, 16, v172
	v_and_b32_e32 v227, 0xffff0000, v172
	v_lshlrev_b32_e32 v228, 16, v173
	v_and_b32_e32 v229, 0xffff0000, v173
	v_lshlrev_b32_e32 v230, 16, v174
	v_and_b32_e32 v231, 0xffff0000, v174
	v_lshlrev_b32_e32 v248, 16, v175
	v_and_b32_e32 v249, 0xffff0000, v175
	v_pk_mul_f32 v[226:227], v[226:227], s[18:19] op_sel_hi:[1,0]
	v_pk_mul_f32 v[228:229], v[228:229], s[18:19] op_sel_hi:[1,0]
	v_pk_mul_f32 v[230:231], v[230:231], s[18:19] op_sel_hi:[1,0]
	v_pk_mul_f32 v[248:249], v[248:249], s[18:19] op_sel_hi:[1,0]
	v_exp_f32_e32 v226, v226
	v_exp_f32_e32 v227, v227
	v_exp_f32_e32 v228, v228
	v_exp_f32_e32 v229, v229
	v_exp_f32_e32 v230, v230
	v_exp_f32_e32 v231, v231
	v_exp_f32_e32 v248, v248
	v_exp_f32_e32 v249, v249
	v_pk_add_f32 v[226:227], v[226:227], s[20:21] op_sel_hi:[1,0]
	v_pk_add_f32 v[228:229], v[228:229], s[20:21] op_sel_hi:[1,0]
	v_pk_add_f32 v[230:231], v[230:231], s[20:21] op_sel_hi:[1,0]
	v_pk_add_f32 v[248:249], v[248:249], s[20:21] op_sel_hi:[1,0]
	v_rcp_f32_e32 v226, v226
	v_rcp_f32_e32 v227, v227
	v_rcp_f32_e32 v228, v228
	v_rcp_f32_e32 v229, v229
	v_rcp_f32_e32 v230, v230
	v_rcp_f32_e32 v231, v231
	v_rcp_f32_e32 v248, v248
	v_rcp_f32_e32 v249, v249
	v_pk_mul_f32 v[226:227], v[226:227], v[90:91]
	v_pk_mul_f32 v[228:229], v[228:229], v[92:93]
	v_pk_mul_f32 v[230:231], v[230:231], v[82:83]
	v_pk_mul_f32 v[248:249], v[248:249], v[84:85]
	v_cvt_pk_bf16_f32 v172, v226, v227
	v_cvt_pk_bf16_f32 v173, v228, v229
	v_cvt_pk_bf16_f32 v174, v230, v231
	v_cvt_pk_bf16_f32 v175, v248, v249
	s_waitcnt vmcnt(8)
; DI unsigned pk_bf16(float lo, float hi) { unsigned r; asm("v_cvt_pk_bf16_f32 %0, %1, %2" : "=v"(r) : "v"(lo), "v"(hi)); return r; }
; DI float lo_f(unsigned w) { return __uint_as_float(w << 16); }
; DI float hi_f(unsigned w) { return __uint_as_float(w & 0xffff0000u); }
; DI float sigmoidf_(float x) { return __builtin_amdgcn_rcpf(1.f + __expf(-x)); }
;     DI void operator()(const f32x4 (&acc)[2][2][4][2], const Unit& u, int wr, int wc, int fr, int fq, LAS unsigned char* lds) const {
;     ...
;                     for (int bj = 0; bj < 2; ++bj) {
;                         bf16_t* gp = Gb + ((rl0 + ai * HALF + m * 16) * (unsigned)IN_DIM + cl0 + bj * HALF);
;                         const u32x4 gv = *(const u32x4*)gp;
;                         const f32x4 v0 = acc[ai][bj][m][0], v1 = acc[ai][bj][m][1];
;                         u32x4 o;
;                         o[0] = pk_bf16(v0[0] * sigmoidf_(lo_f(gv[0])), v0[1] * sigmoidf_(hi_f(gv[0]))); o[1] = pk_bf16(v0[2] * sigmoidf_(lo_f(gv[1])), v0[3] * sigmoidf_(hi_f(gv[1])));
;                         o[2] = pk_bf16(v1[0] * sigmoidf_(lo_f(gv[2])), v1[1] * sigmoidf_(hi_f(gv[2]))); o[3] = pk_bf16(v1[2] * sigmoidf_(lo_f(gv[3])), v1[3] * sigmoidf_(hi_f(gv[3])));
;                         *(u32x4*)gp = o; }
	v_lshlrev_b32_e32 v226, 16, v190
	v_and_b32_e32 v227, 0xffff0000, v190
	v_lshlrev_b32_e32 v228, 16, v191
	v_and_b32_e32 v229, 0xffff0000, v191
	v_lshlrev_b32_e32 v230, 16, v192
	v_and_b32_e32 v231, 0xffff0000, v192
	v_lshlrev_b32_e32 v248, 16, v193
	v_and_b32_e32 v249, 0xffff0000, v193
	v_pk_mul_f32 v[226:227], v[226:227], s[18:19] op_sel_hi:[1,0]
	v_pk_mul_f32 v[228:229], v[228:229], s[18:19] op_sel_hi:[1,0]
	v_pk_mul_f32 v[230:231], v[230:231], s[18:19] op_sel_hi:[1,0]
	v_pk_mul_f32 v[248:249], v[248:249], s[18:19] op_sel_hi:[1,0]
	v_exp_f32_e32 v226, v226
	v_exp_f32_e32 v227, v227
	v_exp_f32_e32 v228, v228
	v_exp_f32_e32 v229, v229
	v_exp_f32_e32 v230, v230
	v_exp_f32_e32 v231, v231
	v_exp_f32_e32 v248, v248
	v_exp_f32_e32 v249, v249
	v_pk_add_f32 v[226:227], v[226:227], s[20:21] op_sel_hi:[1,0]
	v_pk_add_f32 v[228:229], v[228:229], s[20:21] op_sel_hi:[1,0]
	v_pk_add_f32 v[230:231], v[230:231], s[20:21] op_sel_hi:[1,0]
	v_pk_add_f32 v[248:249], v[248:249], s[20:21] op_sel_hi:[1,0]
	v_rcp_f32_e32 v226, v226
	v_rcp_f32_e32 v227, v227
	v_rcp_f32_e32 v228, v228
	v_rcp_f32_e32 v229, v229
	v_rcp_f32_e32 v230, v230
	v_rcp_f32_e32 v231, v231
	v_rcp_f32_e32 v248, v248
	v_rcp_f32_e32 v249, v249
	v_pk_mul_f32 v[226:227], v[226:227], v[70:71]
	v_pk_mul_f32 v[228:229], v[228:229], v[72:73]
	v_pk_mul_f32 v[230:231], v[230:231], v[66:67]
	v_pk_mul_f32 v[248:249], v[248:249], v[68:69]
	v_cvt_pk_bf16_f32 v190, v226, v227
	v_cvt_pk_bf16_f32 v191, v228, v229
	v_cvt_pk_bf16_f32 v192, v230, v231
	v_cvt_pk_bf16_f32 v193, v248, v249
	s_waitcnt vmcnt(7)
	v_lshlrev_b32_e32 v226, 16, v194
	v_and_b32_e32 v227, 0xffff0000, v194
	v_lshlrev_b32_e32 v228, 16, v195
	v_and_b32_e32 v229, 0xffff0000, v195
	v_lshlrev_b32_e32 v230, 16, v196
	v_and_b32_e32 v231, 0xffff0000, v196
	v_lshlrev_b32_e32 v248, 16, v197
	v_and_b32_e32 v249, 0xffff0000, v197
	v_pk_mul_f32 v[226:227], v[226:227], s[18:19] op_sel_hi:[1,0]
	v_pk_mul_f32 v[228:229], v[228:229], s[18:19] op_sel_hi:[1,0]
	v_pk_mul_f32 v[230:231], v[230:231], s[18:19] op_sel_hi:[1,0]
	v_pk_mul_f32 v[248:249], v[248:249], s[18:19] op_sel_hi:[1,0]
	v_exp_f32_e32 v226, v226
	v_exp_f32_e32 v227, v227
	v_exp_f32_e32 v228, v228
	v_exp_f32_e32 v229, v229
	v_exp_f32_e32 v230, v230
	v_exp_f32_e32 v231, v231
	v_exp_f32_e32 v248, v248
	v_exp_f32_e32 v249, v249
	v_pk_add_f32 v[226:227], v[226:227], s[20:21] op_sel_hi:[1,0]
	v_pk_add_f32 v[228:229], v[228:229], s[20:21] op_sel_hi:[1,0]
	v_pk_add_f32 v[230:231], v[230:231], s[20:21] op_sel_hi:[1,0]
	v_pk_add_f32 v[248:249], v[248:249], s[20:21] op_sel_hi:[1,0]
	v_rcp_f32_e32 v226, v226
	v_rcp_f32_e32 v227, v227
	v_rcp_f32_e32 v228, v228
	v_rcp_f32_e32 v229, v229
	v_rcp_f32_e32 v230, v230
	v_rcp_f32_e32 v231, v231
	v_rcp_f32_e32 v248, v248
	v_rcp_f32_e32 v249, v249
	v_pk_mul_f32 v[226:227], v[226:227], v[62:63]
	v_pk_mul_f32 v[228:229], v[228:229], v[64:65]
	v_pk_mul_f32 v[230:231], v[230:231], v[58:59]
	v_pk_mul_f32 v[248:249], v[248:249], v[60:61]
	v_cvt_pk_bf16_f32 v194, v226, v227
	v_cvt_pk_bf16_f32 v195, v228, v229
	v_cvt_pk_bf16_f32 v196, v230, v231
	v_cvt_pk_bf16_f32 v197, v248, v249
	s_waitcnt vmcnt(6)
	v_lshlrev_b32_e32 v226, 16, v198
	v_and_b32_e32 v227, 0xffff0000, v198
	v_lshlrev_b32_e32 v228, 16, v199
	v_and_b32_e32 v229, 0xffff0000, v199
	v_lshlrev_b32_e32 v230, 16, v200
	v_and_b32_e32 v231, 0xffff0000, v200
	v_lshlrev_b32_e32 v248, 16, v201
	v_and_b32_e32 v249, 0xffff0000, v201
	v_pk_mul_f32 v[226:227], v[226:227], s[18:19] op_sel_hi:[1,0]
	v_pk_mul_f32 v[228:229], v[228:229], s[18:19] op_sel_hi:[1,0]
	v_pk_mul_f32 v[230:231], v[230:231], s[18:19] op_sel_hi:[1,0]
	v_pk_mul_f32 v[248:249], v[248:249], s[18:19] op_sel_hi:[1,0]
	v_exp_f32_e32 v226, v226
	v_exp_f32_e32 v227, v227
	v_exp_f32_e32 v228, v228
	v_exp_f32_e32 v229, v229
	v_exp_f32_e32 v230, v230
	v_exp_f32_e32 v231, v231
	v_exp_f32_e32 v248, v248
	v_exp_f32_e32 v249, v249
	v_pk_add_f32 v[226:227], v[226:227], s[20:21] op_sel_hi:[1,0]
	v_pk_add_f32 v[228:229], v[228:229], s[20:21] op_sel_hi:[1,0]
	v_pk_add_f32 v[230:231], v[230:231], s[20:21] op_sel_hi:[1,0]
	v_pk_add_f32 v[248:249], v[248:249], s[20:21] op_sel_hi:[1,0]
	v_rcp_f32_e32 v226, v226
	v_rcp_f32_e32 v227, v227
	v_rcp_f32_e32 v228, v228
	v_rcp_f32_e32 v229, v229
	v_rcp_f32_e32 v230, v230
	v_rcp_f32_e32 v231, v231
	v_rcp_f32_e32 v248, v248
	v_rcp_f32_e32 v249, v249
	v_pk_mul_f32 v[226:227], v[226:227], v[42:43]
	v_pk_mul_f32 v[228:229], v[228:229], v[44:45]
	v_pk_mul_f32 v[230:231], v[230:231], v[34:35]
	v_pk_mul_f32 v[248:249], v[248:249], v[36:37]
	v_cvt_pk_bf16_f32 v198, v226, v227
	v_cvt_pk_bf16_f32 v199, v228, v229
	v_cvt_pk_bf16_f32 v200, v230, v231
	v_cvt_pk_bf16_f32 v201, v248, v249
	s_waitcnt vmcnt(5)
	v_lshlrev_b32_e32 v226, 16, v202
	v_and_b32_e32 v227, 0xffff0000, v202
	v_lshlrev_b32_e32 v228, 16, v203
	v_and_b32_e32 v229, 0xffff0000, v203
	v_lshlrev_b32_e32 v230, 16, v204
	v_and_b32_e32 v231, 0xffff0000, v204
	v_lshlrev_b32_e32 v248, 16, v205
	v_and_b32_e32 v249, 0xffff0000, v205
	v_pk_mul_f32 v[226:227], v[226:227], s[18:19] op_sel_hi:[1,0]
	v_pk_mul_f32 v[228:229], v[228:229], s[18:19] op_sel_hi:[1,0]
	v_pk_mul_f32 v[230:231], v[230:231], s[18:19] op_sel_hi:[1,0]
	v_pk_mul_f32 v[248:249], v[248:249], s[18:19] op_sel_hi:[1,0]
	v_exp_f32_e32 v226, v226
	v_exp_f32_e32 v227, v227
	v_exp_f32_e32 v228, v228
	v_exp_f32_e32 v229, v229
	v_exp_f32_e32 v230, v230
	v_exp_f32_e32 v231, v231
	v_exp_f32_e32 v248, v248
	v_exp_f32_e32 v249, v249
	v_pk_add_f32 v[226:227], v[226:227], s[20:21] op_sel_hi:[1,0]
	v_pk_add_f32 v[228:229], v[228:229], s[20:21] op_sel_hi:[1,0]
	v_pk_add_f32 v[230:231], v[230:231], s[20:21] op_sel_hi:[1,0]
	v_pk_add_f32 v[248:249], v[248:249], s[20:21] op_sel_hi:[1,0]
	v_rcp_f32_e32 v226, v226
	v_rcp_f32_e32 v227, v227
	v_rcp_f32_e32 v228, v228
	v_rcp_f32_e32 v229, v229
	v_rcp_f32_e32 v230, v230
	v_rcp_f32_e32 v231, v231
	v_rcp_f32_e32 v248, v248
	v_rcp_f32_e32 v249, v249
	v_pk_mul_f32 v[226:227], v[226:227], v[54:55]
	v_pk_mul_f32 v[228:229], v[228:229], v[56:57]
	v_pk_mul_f32 v[230:231], v[230:231], v[50:51]
	v_pk_mul_f32 v[248:249], v[248:249], v[52:53]
	v_cvt_pk_bf16_f32 v202, v226, v227
	v_cvt_pk_bf16_f32 v203, v228, v229
	v_cvt_pk_bf16_f32 v204, v230, v231
	v_cvt_pk_bf16_f32 v205, v248, v249
	s_waitcnt vmcnt(4)
; DI unsigned pk_bf16(float lo, float hi) { unsigned r; asm("v_cvt_pk_bf16_f32 %0, %1, %2" : "=v"(r) : "v"(lo), "v"(hi)); return r; }
; DI float lo_f(unsigned w) { return __uint_as_float(w << 16); }
; DI float hi_f(unsigned w) { return __uint_as_float(w & 0xffff0000u); }
; DI float sigmoidf_(float x) { return __builtin_amdgcn_rcpf(1.f + __expf(-x)); }
;     DI void operator()(const f32x4 (&acc)[2][2][4][2], const Unit& u, int wr, int wc, int fr, int fq, LAS unsigned char* lds) const {
;     ...
;                     for (int bj = 0; bj < 2; ++bj) {
;                         bf16_t* gp = Gb + ((rl0 + ai * HALF + m * 16) * (unsigned)IN_DIM + cl0 + bj * HALF);
;                         const u32x4 gv = *(const u32x4*)gp;
;                         const f32x4 v0 = acc[ai][bj][m][0], v1 = acc[ai][bj][m][1];
;                         u32x4 o;
;                         o[0] = pk_bf16(v0[0] * sigmoidf_(lo_f(gv[0])), v0[1] * sigmoidf_(hi_f(gv[0]))); o[1] = pk_bf16(v0[2] * sigmoidf_(lo_f(gv[1])), v0[3] * sigmoidf_(hi_f(gv[1])));
;                         o[2] = pk_bf16(v1[0] * sigmoidf_(lo_f(gv[2])), v1[1] * sigmoidf_(hi_f(gv[2]))); o[3] = pk_bf16(v1[2] * sigmoidf_(lo_f(gv[3])), v1[3] * sigmoidf_(hi_f(gv[3])));
;                         *(u32x4*)gp = o; }
	v_lshlrev_b32_e32 v226, 16, v206
	v_and_b32_e32 v227, 0xffff0000, v206
	v_lshlrev_b32_e32 v228, 16, v207
	v_and_b32_e32 v229, 0xffff0000, v207
	v_lshlrev_b32_e32 v230, 16, v208
	v_and_b32_e32 v231, 0xffff0000, v208
	v_lshlrev_b32_e32 v248, 16, v209
	v_and_b32_e32 v249, 0xffff0000, v209
	v_pk_mul_f32 v[226:227], v[226:227], s[18:19] op_sel_hi:[1,0]
	v_pk_mul_f32 v[228:229], v[228:229], s[18:19] op_sel_hi:[1,0]
	v_pk_mul_f32 v[230:231], v[230:231], s[18:19] op_sel_hi:[1,0]
	v_pk_mul_f32 v[248:249], v[248:249], s[18:19] op_sel_hi:[1,0]
	v_exp_f32_e32 v226, v226
	v_exp_f32_e32 v227, v227
	v_exp_f32_e32 v228, v228
	v_exp_f32_e32 v229, v229
	v_exp_f32_e32 v230, v230
	v_exp_f32_e32 v231, v231
	v_exp_f32_e32 v248, v248
	v_exp_f32_e32 v249, v249
	v_pk_add_f32 v[226:227], v[226:227], s[20:21] op_sel_hi:[1,0]
	v_pk_add_f32 v[228:229], v[228:229], s[20:21] op_sel_hi:[1,0]
	v_pk_add_f32 v[230:231], v[230:231], s[20:21] op_sel_hi:[1,0]
	v_pk_add_f32 v[248:249], v[248:249], s[20:21] op_sel_hi:[1,0]
	v_rcp_f32_e32 v226, v226
	v_rcp_f32_e32 v227, v227
	v_rcp_f32_e32 v228, v228
	v_rcp_f32_e32 v229, v229
	v_rcp_f32_e32 v230, v230
	v_rcp_f32_e32 v231, v231
	v_rcp_f32_e32 v248, v248
	v_rcp_f32_e32 v249, v249
	v_pk_mul_f32 v[226:227], v[226:227], v[26:27]
	v_pk_mul_f32 v[228:229], v[228:229], v[28:29]
	v_pk_mul_f32 v[230:231], v[230:231], v[18:19]
	v_pk_mul_f32 v[248:249], v[248:249], v[20:21]
	v_cvt_pk_bf16_f32 v206, v226, v227
	v_cvt_pk_bf16_f32 v207, v228, v229
	v_cvt_pk_bf16_f32 v208, v230, v231
	v_cvt_pk_bf16_f32 v209, v248, v249
	s_waitcnt vmcnt(3)
	v_lshlrev_b32_e32 v226, 16, v210
	v_and_b32_e32 v227, 0xffff0000, v210
	v_lshlrev_b32_e32 v228, 16, v211
	v_and_b32_e32 v229, 0xffff0000, v211
	v_lshlrev_b32_e32 v230, 16, v212
	v_and_b32_e32 v231, 0xffff0000, v212
	v_lshlrev_b32_e32 v248, 16, v213
	v_and_b32_e32 v249, 0xffff0000, v213
	v_pk_mul_f32 v[226:227], v[226:227], s[18:19] op_sel_hi:[1,0]
	v_pk_mul_f32 v[228:229], v[228:229], s[18:19] op_sel_hi:[1,0]
	v_pk_mul_f32 v[230:231], v[230:231], s[18:19] op_sel_hi:[1,0]
	v_pk_mul_f32 v[248:249], v[248:249], s[18:19] op_sel_hi:[1,0]
	v_exp_f32_e32 v226, v226
	v_exp_f32_e32 v227, v227
	v_exp_f32_e32 v228, v228
	v_exp_f32_e32 v229, v229
	v_exp_f32_e32 v230, v230
	v_exp_f32_e32 v231, v231
	v_exp_f32_e32 v248, v248
	v_exp_f32_e32 v249, v249
	v_pk_add_f32 v[226:227], v[226:227], s[20:21] op_sel_hi:[1,0]
	v_pk_add_f32 v[228:229], v[228:229], s[20:21] op_sel_hi:[1,0]
	v_pk_add_f32 v[230:231], v[230:231], s[20:21] op_sel_hi:[1,0]
	v_pk_add_f32 v[248:249], v[248:249], s[20:21] op_sel_hi:[1,0]
	v_rcp_f32_e32 v226, v226
	v_rcp_f32_e32 v227, v227
	v_rcp_f32_e32 v228, v228
	v_rcp_f32_e32 v229, v229
	v_rcp_f32_e32 v230, v230
	v_rcp_f32_e32 v231, v231
	v_rcp_f32_e32 v248, v248
	v_rcp_f32_e32 v249, v249
	v_pk_mul_f32 v[226:227], v[226:227], v[46:47]
	v_pk_mul_f32 v[228:229], v[228:229], v[48:49]
	v_pk_mul_f32 v[230:231], v[230:231], v[38:39]
	v_pk_mul_f32 v[248:249], v[248:249], v[40:41]
	v_cvt_pk_bf16_f32 v210, v226, v227
	v_cvt_pk_bf16_f32 v211, v228, v229
	v_cvt_pk_bf16_f32 v212, v230, v231
	v_cvt_pk_bf16_f32 v213, v248, v249
	s_waitcnt vmcnt(2)
	v_lshlrev_b32_e32 v226, 16, v214
	v_and_b32_e32 v227, 0xffff0000, v214
	v_lshlrev_b32_e32 v228, 16, v215
	v_and_b32_e32 v229, 0xffff0000, v215
	v_lshlrev_b32_e32 v230, 16, v216
	v_and_b32_e32 v231, 0xffff0000, v216
	v_lshlrev_b32_e32 v248, 16, v217
	v_and_b32_e32 v249, 0xffff0000, v217
	v_pk_mul_f32 v[226:227], v[226:227], s[18:19] op_sel_hi:[1,0]
	v_pk_mul_f32 v[228:229], v[228:229], s[18:19] op_sel_hi:[1,0]
	v_pk_mul_f32 v[230:231], v[230:231], s[18:19] op_sel_hi:[1,0]
	v_pk_mul_f32 v[248:249], v[248:249], s[18:19] op_sel_hi:[1,0]
	v_exp_f32_e32 v226, v226
	v_exp_f32_e32 v227, v227
	v_exp_f32_e32 v228, v228
	v_exp_f32_e32 v229, v229
	v_exp_f32_e32 v230, v230
	v_exp_f32_e32 v231, v231
	v_exp_f32_e32 v248, v248
	v_exp_f32_e32 v249, v249
	v_pk_add_f32 v[226:227], v[226:227], s[20:21] op_sel_hi:[1,0]
	v_pk_add_f32 v[228:229], v[228:229], s[20:21] op_sel_hi:[1,0]
	v_pk_add_f32 v[230:231], v[230:231], s[20:21] op_sel_hi:[1,0]
	v_pk_add_f32 v[248:249], v[248:249], s[20:21] op_sel_hi:[1,0]
	v_rcp_f32_e32 v226, v226
	v_rcp_f32_e32 v227, v227
	v_rcp_f32_e32 v228, v228
	v_rcp_f32_e32 v229, v229
	v_rcp_f32_e32 v230, v230
	v_rcp_f32_e32 v231, v231
	v_rcp_f32_e32 v248, v248
	v_rcp_f32_e32 v249, v249
	v_pk_mul_f32 v[226:227], v[226:227], v[14:15]
	v_pk_mul_f32 v[228:229], v[228:229], v[16:17]
	v_pk_mul_f32 v[230:231], v[230:231], v[10:11]
	v_pk_mul_f32 v[248:249], v[248:249], v[12:13]
	v_cvt_pk_bf16_f32 v214, v226, v227
	v_cvt_pk_bf16_f32 v215, v228, v229
	v_cvt_pk_bf16_f32 v216, v230, v231
	v_cvt_pk_bf16_f32 v217, v248, v249
	s_waitcnt vmcnt(1)
; DI unsigned pk_bf16(float lo, float hi) { unsigned r; asm("v_cvt_pk_bf16_f32 %0, %1, %2" : "=v"(r) : "v"(lo), "v"(hi)); return r; }
; DI float lo_f(unsigned w) { return __uint_as_float(w << 16); }
; DI float hi_f(unsigned w) { return __uint_as_float(w & 0xffff0000u); }
; DI float sigmoidf_(float x) { return __builtin_amdgcn_rcpf(1.f + __expf(-x)); }
;     DI void operator()(const f32x4 (&acc)[2][2][4][2], const Unit& u, int wr, int wc, int fr, int fq, LAS unsigned char* lds) const {
;     ...
;                     for (int bj = 0; bj < 2; ++bj) {
;                         bf16_t* gp = Gb + ((rl0 + ai * HALF + m * 16) * (unsigned)IN_DIM + cl0 + bj * HALF);
;                         const u32x4 gv = *(const u32x4*)gp;
;                         const f32x4 v0 = acc[ai][bj][m][0], v1 = acc[ai][bj][m][1];
;                         u32x4 o;
;                         o[0] = pk_bf16(v0[0] * sigmoidf_(lo_f(gv[0])), v0[1] * sigmoidf_(hi_f(gv[0]))); o[1] = pk_bf16(v0[2] * sigmoidf_(lo_f(gv[1])), v0[3] * sigmoidf_(hi_f(gv[1])));
;                         o[2] = pk_bf16(v1[0] * sigmoidf_(lo_f(gv[2])), v1[1] * sigmoidf_(hi_f(gv[2]))); o[3] = pk_bf16(v1[2] * sigmoidf_(lo_f(gv[3])), v1[3] * sigmoidf_(hi_f(gv[3])));
;                         *(u32x4*)gp = o; }
	v_lshlrev_b32_e32 v226, 16, v218
	v_and_b32_e32 v227, 0xffff0000, v218
	v_lshlrev_b32_e32 v228, 16, v219
	v_and_b32_e32 v229, 0xffff0000, v219
	v_lshlrev_b32_e32 v230, 16, v220
	v_and_b32_e32 v231, 0xffff0000, v220
	v_lshlrev_b32_e32 v248, 16, v221
	v_and_b32_e32 v249, 0xffff0000, v221
	v_pk_mul_f32 v[226:227], v[226:227], s[18:19] op_sel_hi:[1,0]
	v_pk_mul_f32 v[228:229], v[228:229], s[18:19] op_sel_hi:[1,0]
	v_pk_mul_f32 v[230:231], v[230:231], s[18:19] op_sel_hi:[1,0]
	v_pk_mul_f32 v[248:249], v[248:249], s[18:19] op_sel_hi:[1,0]
	v_exp_f32_e32 v226, v226
	v_exp_f32_e32 v227, v227
	v_exp_f32_e32 v228, v228
	v_exp_f32_e32 v229, v229
	v_exp_f32_e32 v230, v230
	v_exp_f32_e32 v231, v231
	v_exp_f32_e32 v248, v248
	v_exp_f32_e32 v249, v249
	v_pk_add_f32 v[226:227], v[226:227], s[20:21] op_sel_hi:[1,0]
	v_pk_add_f32 v[228:229], v[228:229], s[20:21] op_sel_hi:[1,0]
	v_pk_add_f32 v[230:231], v[230:231], s[20:21] op_sel_hi:[1,0]
	v_pk_add_f32 v[248:249], v[248:249], s[20:21] op_sel_hi:[1,0]
	v_rcp_f32_e32 v226, v226
	v_rcp_f32_e32 v227, v227
	v_rcp_f32_e32 v228, v228
	v_rcp_f32_e32 v229, v229
	v_rcp_f32_e32 v230, v230
	v_rcp_f32_e32 v231, v231
	v_rcp_f32_e32 v248, v248
	v_rcp_f32_e32 v249, v249
	v_pk_mul_f32 v[226:227], v[226:227], v[30:31]
	v_pk_mul_f32 v[228:229], v[228:229], v[32:33]
	v_pk_mul_f32 v[230:231], v[230:231], v[22:23]
	v_pk_mul_f32 v[248:249], v[248:249], v[24:25]
	v_cvt_pk_bf16_f32 v218, v226, v227
	v_cvt_pk_bf16_f32 v219, v228, v229
	v_cvt_pk_bf16_f32 v220, v230, v231
	v_cvt_pk_bf16_f32 v221, v248, v249
	s_waitcnt vmcnt(0)
	v_lshlrev_b32_e32 v226, 16, v222
	v_and_b32_e32 v227, 0xffff0000, v222
	v_lshlrev_b32_e32 v228, 16, v223
	v_and_b32_e32 v229, 0xffff0000, v223
	v_lshlrev_b32_e32 v230, 16, v224
	v_and_b32_e32 v231, 0xffff0000, v224
	v_lshlrev_b32_e32 v248, 16, v225
	v_and_b32_e32 v249, 0xffff0000, v225
	v_pk_mul_f32 v[226:227], v[226:227], s[18:19] op_sel_hi:[1,0]
	v_pk_mul_f32 v[228:229], v[228:229], s[18:19] op_sel_hi:[1,0]
	v_pk_mul_f32 v[230:231], v[230:231], s[18:19] op_sel_hi:[1,0]
	v_pk_mul_f32 v[248:249], v[248:249], s[18:19] op_sel_hi:[1,0]
	v_exp_f32_e32 v226, v226
	v_exp_f32_e32 v227, v227
	v_exp_f32_e32 v228, v228
	v_exp_f32_e32 v229, v229
	v_exp_f32_e32 v230, v230
	v_exp_f32_e32 v231, v231
	v_exp_f32_e32 v248, v248
	v_exp_f32_e32 v249, v249
	v_pk_add_f32 v[226:227], v[226:227], s[20:21] op_sel_hi:[1,0]
	v_pk_add_f32 v[228:229], v[228:229], s[20:21] op_sel_hi:[1,0]
	v_pk_add_f32 v[230:231], v[230:231], s[20:21] op_sel_hi:[1,0]
	v_pk_add_f32 v[248:249], v[248:249], s[20:21] op_sel_hi:[1,0]
	v_rcp_f32_e32 v226, v226
	v_rcp_f32_e32 v227, v227
	v_rcp_f32_e32 v228, v228
	v_rcp_f32_e32 v229, v229
	v_rcp_f32_e32 v230, v230
	v_rcp_f32_e32 v231, v231
	v_rcp_f32_e32 v248, v248
	v_rcp_f32_e32 v249, v249
	v_pk_mul_f32 v[226:227], v[226:227], v[6:7]
	v_pk_mul_f32 v[228:229], v[228:229], v[8:9]
	v_pk_mul_f32 v[230:231], v[230:231], v[2:3]
	v_pk_mul_f32 v[248:249], v[248:249], v[4:5]
	v_cvt_pk_bf16_f32 v222, v226, v227
	v_cvt_pk_bf16_f32 v223, v228, v229
	v_cvt_pk_bf16_f32 v224, v230, v231
	v_cvt_pk_bf16_f32 v225, v248, v249
	global_store_dwordx4 v130, v[148:151], s[42:43]
	global_store_dwordx4 v130, v[152:155], s[42:43] offset:256
	global_store_dwordx4 v131, v[156:159], s[42:43]
	global_store_dwordx4 v131, v[160:163], s[42:43] offset:256
	global_store_dwordx4 v132, v[164:167], s[42:43]
	global_store_dwordx4 v132, v[168:171], s[42:43] offset:256
	global_store_dwordx4 v133, v[172:175], s[42:43]
	global_store_dwordx4 v133, v[190:193], s[42:43] offset:256
	global_store_dwordx4 v179, v[194:197], s[42:43]
	global_store_dwordx4 v179, v[198:201], s[42:43] offset:256
	global_store_dwordx4 v180, v[202:205], s[42:43]
	global_store_dwordx4 v180, v[206:209], s[42:43] offset:256
	global_store_dwordx4 v240, v[210:213], s[42:43]
	global_store_dwordx4 v240, v[214:217], s[42:43] offset:256
	global_store_dwordx4 v241, v[218:221], s[42:43]
	global_store_dwordx4 v241, v[222:225], s[42:43] offset:256
